# ATTN softmax: xor-8/4/2/1 butterfly steps via DPP row_ror instead of ds_bpermute (bit-identical)
# speedup vs baseline: 1.0110x; 1.0040x over previous
; DI void attn_item(const P& p, int b, int kvh, int quad4, char* smem, const AttnPre& pre) {
;     ...
;   float pr[4][4];
; #pragma unroll
;   for (int h = 0; h < 4; ++h) {
;     float m = -INFINITY;
; #pragma unroll
;     for (int j = 0; j < 4; ++j) { pr[h][j] = L[h * 256 + lane + 64 * j]; m = fmaxf(m, pr[h][j]); }
; #pragma unroll
;     for (int off = 32; off >= 1; off >>= 1) m = fmaxf(m, __shfl_xor(m, off));
;     float sum = 0.f;
; #pragma unroll
;     for (int j = 0; j < 4; ++j) { pr[h][j] = __expf(pr[h][j] - m); sum += pr[h][j]; }
; #pragma unroll
;     for (int off = 32; off >= 1; off >>= 1) sum += __shfl_xor(sum, off);
.LBB0_345:
	s_or_b64 exec, exec, s[6:7]
	s_nop 3
	v_mbcnt_hi_u32_b32 v20, -1, v222
	v_and_b32_e32 v16, 64, v20
	v_add_u32_e32 v21, 64, v16
	ds_read2st64_b32 v[16:17], v106 offset1:1
	ds_read2st64_b32 v[18:19], v106 offset0:2 offset1:3
	ds_read2st64_b32 v[26:27], v106 offset0:6 offset1:7
	ds_read2st64_b32 v[42:43], v106 offset0:14 offset1:15
	v_xor_b32_e32 v23, 32, v20
	s_mov_b32 s6, 0xff800000
	v_cmp_lt_i32_e32 vcc, v23, v21
	s_waitcnt lgkmcnt(3)
	v_max3_f32 v22, v16, s6, v17
	s_waitcnt lgkmcnt(2)
	v_max3_f32 v22, v22, v18, v19
	v_cndmask_b32_e32 v23, v20, v23, vcc
	v_lshlrev_b32_e32 v84, 2, v23
	ds_bpermute_b32 v23, v84, v22
	v_lshlrev_b32_e32 v192, 3, v105
	ds_read2st64_b32 v[40:41], v106 offset0:12 offset1:13
	s_waitcnt lgkmcnt(1)
	v_max_f32_e32 v23, v23, v23
	v_max_f32_e32 v22, v22, v23
	v_xor_b32_e32 v23, 16, v20
	v_cmp_lt_i32_e32 vcc, v23, v21
	s_nop 1
	v_cndmask_b32_e32 v23, v20, v23, vcc
	v_lshlrev_b32_e32 v85, 2, v23
	ds_bpermute_b32 v23, v85, v22
	s_waitcnt lgkmcnt(0)
	v_max_f32_e32 v23, v23, v23
	v_max_f32_e32 v22, v22, v23
	v_xor_b32_e32 v23, 8, v20
	v_cmp_lt_i32_e32 vcc, v23, v21
	s_nop 1
	v_cndmask_b32_e32 v23, v20, v23, vcc
	v_lshlrev_b32_e32 v39, 2, v23
	s_nop 1
	v_mov_b32_dpp v23, v22 row_ror:8 row_mask:0xf bank_mask:0xf
	s_waitcnt lgkmcnt(0)
	v_max_f32_e32 v23, v23, v23
	v_max_f32_e32 v22, v22, v23
	v_xor_b32_e32 v23, 4, v20
	v_cmp_lt_i32_e32 vcc, v23, v21
	s_nop 1
	v_cndmask_b32_e32 v23, v20, v23, vcc
	v_lshlrev_b32_e32 v38, 2, v23
	s_nop 1
	v_mov_b32_dpp v23, v22 row_ror:4 row_mask:0xf bank_mask:0xf
	s_waitcnt lgkmcnt(0)
	v_max_f32_e32 v23, v23, v23
	v_max_f32_e32 v22, v22, v23
	v_xor_b32_e32 v23, 2, v20
	v_cmp_lt_i32_e32 vcc, v23, v21
	s_nop 1
	v_cndmask_b32_e32 v23, v20, v23, vcc
	v_lshlrev_b32_e32 v37, 2, v23
	s_nop 1
	v_mov_b32_dpp v23, v22 row_ror:2 row_mask:0xf bank_mask:0xf
	s_waitcnt lgkmcnt(0)
	v_max_f32_e32 v23, v23, v23
	v_max_f32_e32 v22, v22, v23
	v_xor_b32_e32 v23, 1, v20
	v_cmp_lt_i32_e32 vcc, v23, v21
	s_nop 1
	v_cndmask_b32_e32 v20, v20, v23, vcc
	v_lshlrev_b32_e32 v36, 2, v20
	s_nop 1
	v_mov_b32_dpp v20, v22 row_ror:1 row_mask:0xf bank_mask:0xf
	s_waitcnt lgkmcnt(0)
	v_max_f32_e32 v20, v20, v20
	v_max_f32_e32 v20, v22, v20
	v_sub_f32_e32 v17, v17, v20
	v_mul_f32_e32 v17, 0x3fb8aa3b, v17
	v_exp_f32_e32 v24, v17
	v_sub_f32_e32 v17, v18, v20
	v_mul_f32_e32 v17, 0x3fb8aa3b, v17
	v_exp_f32_e32 v22, v17
	v_sub_f32_e32 v17, v19, v20
	ds_read2st64_b32 v[18:19], v106 offset0:4 offset1:5
	v_mul_f32_e32 v17, 0x3fb8aa3b, v17
	v_sub_f32_e32 v16, v16, v20
	v_exp_f32_e32 v20, v17
	v_mul_f32_e32 v16, 0x3fb8aa3b, v16
	s_waitcnt lgkmcnt(0)
	v_max3_f32 v17, v18, s6, v19
	v_max3_f32 v17, v17, v26, v27
	ds_bpermute_b32 v21, v84, v17
	v_exp_f32_e32 v16, v16
	s_waitcnt lgkmcnt(0)
	v_max_f32_e32 v21, v21, v21
	v_max_f32_e32 v17, v17, v21
	ds_bpermute_b32 v21, v85, v17
	s_waitcnt lgkmcnt(0)
	v_max_f32_e32 v21, v21, v21
	v_max_f32_e32 v17, v17, v21
	s_nop 1
	v_mov_b32_dpp v21, v17 row_ror:8 row_mask:0xf bank_mask:0xf
	s_waitcnt lgkmcnt(0)
	v_max_f32_e32 v21, v21, v21
	v_max_f32_e32 v17, v17, v21
	s_nop 1
	v_mov_b32_dpp v21, v17 row_ror:4 row_mask:0xf bank_mask:0xf
	s_waitcnt lgkmcnt(0)
	v_max_f32_e32 v21, v21, v21
	v_max_f32_e32 v17, v17, v21
	s_nop 1
	v_mov_b32_dpp v21, v17 row_ror:2 row_mask:0xf bank_mask:0xf
	s_waitcnt lgkmcnt(0)
	v_max_f32_e32 v21, v21, v21
	v_max_f32_e32 v17, v17, v21
	s_nop 1
	v_mov_b32_dpp v21, v17 row_ror:1 row_mask:0xf bank_mask:0xf
	s_waitcnt lgkmcnt(0)
	v_max_f32_e32 v21, v21, v21
	v_max_f32_e32 v21, v17, v21
	v_sub_f32_e32 v17, v18, v21
	v_sub_f32_e32 v18, v19, v21
	v_mul_f32_e32 v18, 0x3fb8aa3b, v18
	v_exp_f32_e32 v25, v18
	v_sub_f32_e32 v18, v26, v21
	v_mul_f32_e32 v18, 0x3fb8aa3b, v18
	v_exp_f32_e32 v23, v18
	v_sub_f32_e32 v18, v27, v21
	v_mul_f32_e32 v18, 0x3fb8aa3b, v18
	v_exp_f32_e32 v21, v18
	ds_read2st64_b32 v[18:19], v106 offset0:8 offset1:9
	ds_read2st64_b32 v[26:27], v106 offset0:10 offset1:11
	v_mul_f32_e32 v17, 0x3fb8aa3b, v17
	v_exp_f32_e32 v17, v17
	s_waitcnt lgkmcnt(1)
	v_max3_f32 v28, v18, s6, v19
	s_waitcnt lgkmcnt(0)
	v_max3_f32 v28, v28, v26, v27
	ds_bpermute_b32 v29, v84, v28
	v_pk_add_f32 v[32:33], v[16:17], 0 op_sel_hi:[1,0]
	s_waitcnt lgkmcnt(0)
	v_max_f32_e32 v29, v29, v29
	v_max_f32_e32 v28, v28, v29
	ds_bpermute_b32 v29, v85, v28
	v_pk_add_f32 v[32:33], v[24:25], v[32:33]
	s_waitcnt lgkmcnt(0)
	v_max_f32_e32 v29, v29, v29
	v_max_f32_e32 v28, v28, v29
	s_nop 1
	v_mov_b32_dpp v29, v28 row_ror:8 row_mask:0xf bank_mask:0xf
	v_pk_add_f32 v[32:33], v[22:23], v[32:33]
	s_waitcnt lgkmcnt(0)
	v_max_f32_e32 v29, v29, v29
	v_max_f32_e32 v28, v28, v29
	s_nop 1
	v_mov_b32_dpp v29, v28 row_ror:4 row_mask:0xf bank_mask:0xf
	v_pk_add_f32 v[32:33], v[20:21], v[32:33]
	s_waitcnt lgkmcnt(0)
	v_max_f32_e32 v29, v29, v29
	v_max_f32_e32 v28, v28, v29
	s_nop 1
	v_mov_b32_dpp v29, v28 row_ror:2 row_mask:0xf bank_mask:0xf
	s_waitcnt lgkmcnt(0)
	v_max_f32_e32 v29, v29, v29
	v_max_f32_e32 v28, v28, v29
	s_nop 1
	v_mov_b32_dpp v29, v28 row_ror:1 row_mask:0xf bank_mask:0xf
	s_waitcnt lgkmcnt(0)
	v_max_f32_e32 v29, v29, v29
	v_max_f32_e32 v29, v28, v29
	v_sub_f32_e32 v19, v19, v29
	v_mul_f32_e32 v19, 0x3fb8aa3b, v19
	v_exp_f32_e32 v30, v19
	v_sub_f32_e32 v19, v26, v29
	v_mul_f32_e32 v19, 0x3fb8aa3b, v19
	v_exp_f32_e32 v28, v19
	v_sub_f32_e32 v19, v27, v29
	v_mul_f32_e32 v19, 0x3fb8aa3b, v19
	v_exp_f32_e32 v26, v19
	v_max3_f32 v19, v40, s6, v41
	v_max3_f32 v19, v19, v42, v43
	ds_bpermute_b32 v27, v84, v19
	v_sub_f32_e32 v18, v18, v29
	v_mul_f32_e32 v18, 0x3fb8aa3b, v18
	v_exp_f32_e32 v18, v18
	s_waitcnt lgkmcnt(0)
	v_max_f32_e32 v27, v27, v27
	v_max_f32_e32 v19, v19, v27
	ds_bpermute_b32 v27, v85, v19
	s_waitcnt lgkmcnt(0)
; DI void attn_item(const P& p, int b, int kvh, int quad4, char* smem, const AttnPre& pre) {
;     ...
;   for (int h = 0; h < 4; ++h) {
;     float m = -INFINITY;
; #pragma unroll
;     for (int j = 0; j < 4; ++j) { pr[h][j] = L[h * 256 + lane + 64 * j]; m = fmaxf(m, pr[h][j]); }
; #pragma unroll
;     for (int off = 32; off >= 1; off >>= 1) m = fmaxf(m, __shfl_xor(m, off));
;     float sum = 0.f;
; #pragma unroll
;     for (int j = 0; j < 4; ++j) { pr[h][j] = __expf(pr[h][j] - m); sum += pr[h][j]; }
; #pragma unroll
;     for (int off = 32; off >= 1; off >>= 1) sum += __shfl_xor(sum, off);
;     const float inv = 1.f / sum;
; #pragma unroll
;     for (int j = 0; j < 4; ++j) pr[h][j] *= inv;
;   }
;   __builtin_amdgcn_wave_barrier();
; #pragma unroll
;   for (int j = 0; j < 4; ++j) *(float4*)(L + (lane + 64 * j) * 4) = make_float4(pr[0][j], pr[1][j], pr[2][j], pr[3][j]);
;   __builtin_amdgcn_wave_barrier();
;   float o[4][8];
; #pragma unroll
;   for (int h = 0; h < 4; ++h)
; #pragma unroll
;     for (int e = 0; e < 8; ++e) o[h][e] = 0.f;
;   const unsigned char* vb = p.v8 + ((size_t)b * SEQ) * 256 + kvh * 128 + r * 8;
	v_max_f32_e32 v27, v27, v27
	v_max_f32_e32 v19, v19, v27
	s_nop 1
	v_mov_b32_dpp v27, v19 row_ror:8 row_mask:0xf bank_mask:0xf
	s_waitcnt lgkmcnt(0)
	v_max_f32_e32 v27, v27, v27
	v_max_f32_e32 v19, v19, v27
	s_nop 1
	v_mov_b32_dpp v27, v19 row_ror:4 row_mask:0xf bank_mask:0xf
	s_waitcnt lgkmcnt(0)
	v_max_f32_e32 v27, v27, v27
	v_max_f32_e32 v19, v19, v27
	s_nop 1
	v_mov_b32_dpp v27, v19 row_ror:2 row_mask:0xf bank_mask:0xf
	s_waitcnt lgkmcnt(0)
	v_max_f32_e32 v27, v27, v27
	v_max_f32_e32 v19, v19, v27
	s_nop 1
	v_mov_b32_dpp v27, v19 row_ror:1 row_mask:0xf bank_mask:0xf
	s_waitcnt lgkmcnt(0)
	v_max_f32_e32 v27, v27, v27
	v_max_f32_e32 v27, v19, v27
	v_sub_f32_e32 v19, v40, v27
	v_sub_f32_e32 v29, v41, v27
	ds_bpermute_b32 v40, v84, v32
	ds_bpermute_b32 v41, v84, v33
	v_mul_f32_e32 v29, 0x3fb8aa3b, v29
	v_exp_f32_e32 v31, v29
	v_sub_f32_e32 v29, v42, v27
	v_sub_f32_e32 v27, v43, v27
	s_waitcnt lgkmcnt(0)
	v_pk_add_f32 v[32:33], v[32:33], v[40:41]
	ds_bpermute_b32 v40, v85, v32
	ds_bpermute_b32 v41, v85, v33
	v_mul_f32_e32 v19, 0x3fb8aa3b, v19
	v_exp_f32_e32 v19, v19
	v_mul_f32_e32 v29, 0x3fb8aa3b, v29
	v_exp_f32_e32 v29, v29
	s_waitcnt lgkmcnt(0)
	v_pk_add_f32 v[32:33], v[32:33], v[40:41]
	s_nop 1
	v_mov_b32_dpp v40, v32 row_ror:8 row_mask:0xf bank_mask:0xf
	s_nop 1
	v_mov_b32_dpp v41, v33 row_ror:8 row_mask:0xf bank_mask:0xf
	v_mul_f32_e32 v27, 0x3fb8aa3b, v27
	v_exp_f32_e32 v27, v27
	v_pk_add_f32 v[34:35], v[18:19], 0 op_sel_hi:[1,0]
	s_waitcnt lgkmcnt(0)
	v_pk_add_f32 v[32:33], v[32:33], v[40:41]
	s_nop 1
	v_mov_b32_dpp v40, v32 row_ror:4 row_mask:0xf bank_mask:0xf
	s_nop 1
	v_mov_b32_dpp v41, v33 row_ror:4 row_mask:0xf bank_mask:0xf
	v_pk_add_f32 v[34:35], v[30:31], v[34:35]
	s_waitcnt lgkmcnt(0)
	v_pk_add_f32 v[32:33], v[32:33], v[40:41]
	s_nop 1
	v_mov_b32_dpp v40, v32 row_ror:2 row_mask:0xf bank_mask:0xf
	s_nop 1
	v_mov_b32_dpp v41, v33 row_ror:2 row_mask:0xf bank_mask:0xf
	v_pk_add_f32 v[34:35], v[28:29], v[34:35]
	s_waitcnt lgkmcnt(0)
	v_pk_add_f32 v[32:33], v[32:33], v[40:41]
	s_nop 1
	v_mov_b32_dpp v40, v32 row_ror:1 row_mask:0xf bank_mask:0xf
	s_nop 1
	v_mov_b32_dpp v41, v33 row_ror:1 row_mask:0xf bank_mask:0xf
	v_pk_add_f32 v[34:35], v[26:27], v[34:35]
	s_waitcnt lgkmcnt(0)
	v_pk_add_f32 v[32:33], v[32:33], v[40:41]
	s_nop 0
	v_div_scale_f32 v40, s[6:7], v33, v33, 1.0
	v_rcp_f32_e32 v41, v40
	s_nop 0
	v_fma_f32 v42, -v40, v41, 1.0
	v_fmac_f32_e32 v41, v42, v41
	v_div_scale_f32 v42, vcc, 1.0, v33, 1.0
	v_mul_f32_e32 v43, v42, v41
	v_fma_f32 v44, -v40, v43, v42
	v_fmac_f32_e32 v43, v44, v41
	v_fma_f32 v40, -v40, v43, v42
	v_div_fmas_f32 v40, v40, v41, v43
	v_div_fixup_f32 v33, v40, v33, 1.0
	v_div_scale_f32 v40, s[6:7], v32, v32, 1.0
	v_rcp_f32_e32 v41, v40
	s_nop 0
	v_fma_f32 v42, -v40, v41, 1.0
	v_fmac_f32_e32 v41, v42, v41
	v_div_scale_f32 v42, vcc, 1.0, v32, 1.0
	v_mul_f32_e32 v43, v42, v41
	v_fma_f32 v44, -v40, v43, v42
	v_fmac_f32_e32 v43, v44, v41
	v_fma_f32 v40, -v40, v43, v42
	v_div_fmas_f32 v40, v40, v41, v43
	v_div_fixup_f32 v32, v40, v32, 1.0
	ds_bpermute_b32 v40, v84, v34
	ds_bpermute_b32 v41, v84, v35
	v_pk_mul_f32 v[16:17], v[16:17], v[32:33]
	s_waitcnt lgkmcnt(0)
	v_pk_add_f32 v[34:35], v[34:35], v[40:41]
	ds_bpermute_b32 v40, v85, v34
	ds_bpermute_b32 v41, v85, v35
	s_waitcnt lgkmcnt(0)
	v_pk_add_f32 v[34:35], v[34:35], v[40:41]
	s_nop 1
	v_mov_b32_dpp v40, v34 row_ror:8 row_mask:0xf bank_mask:0xf
	s_nop 1
	v_mov_b32_dpp v41, v35 row_ror:8 row_mask:0xf bank_mask:0xf
	s_waitcnt lgkmcnt(0)
	v_pk_add_f32 v[34:35], v[34:35], v[40:41]
	s_nop 1
	v_mov_b32_dpp v40, v34 row_ror:4 row_mask:0xf bank_mask:0xf
	s_nop 1
	v_mov_b32_dpp v41, v35 row_ror:4 row_mask:0xf bank_mask:0xf
	s_waitcnt lgkmcnt(0)
	v_pk_add_f32 v[34:35], v[34:35], v[40:41]
	s_nop 1
	v_mov_b32_dpp v38, v34 row_ror:2 row_mask:0xf bank_mask:0xf
	s_nop 1
	v_mov_b32_dpp v39, v35 row_ror:2 row_mask:0xf bank_mask:0xf
	s_waitcnt lgkmcnt(0)
	v_pk_add_f32 v[34:35], v[34:35], v[38:39]
	s_nop 1
	v_mov_b32_dpp v38, v34 row_ror:1 row_mask:0xf bank_mask:0xf
	s_nop 1
	v_mov_b32_dpp v39, v35 row_ror:1 row_mask:0xf bank_mask:0xf
	s_waitcnt lgkmcnt(0)
	v_pk_add_f32 v[34:35], v[34:35], v[38:39]
	s_nop 0
	v_div_scale_f32 v36, s[6:7], v35, v35, 1.0
	v_rcp_f32_e32 v37, v36
	s_nop 0
	v_fma_f32 v38, -v36, v37, 1.0
	v_fmac_f32_e32 v37, v38, v37
	v_div_scale_f32 v38, vcc, 1.0, v35, 1.0
	v_mul_f32_e32 v39, v38, v37
	v_fma_f32 v40, -v36, v39, v38
	v_fmac_f32_e32 v39, v40, v37
	v_fma_f32 v36, -v36, v39, v38
	v_div_fmas_f32 v36, v36, v37, v39
	v_div_fixup_f32 v35, v36, v35, 1.0
	v_div_scale_f32 v36, s[6:7], v34, v34, 1.0
	v_rcp_f32_e32 v37, v36
	v_readlane_b32 s6, v250, 15
	s_add_u32 s6, s6, s10
	v_readlane_b32 s7, v250, 16
	v_fma_f32 v38, -v36, v37, 1.0
	v_fmac_f32_e32 v37, v38, v37
	v_div_scale_f32 v38, vcc, 1.0, v34, 1.0
	v_mul_f32_e32 v39, v38, v37
	v_fma_f32 v40, -v36, v39, v38
	v_fmac_f32_e32 v39, v40, v37
	v_fma_f32 v36, -v36, v39, v38
	v_div_fmas_f32 v36, v36, v37, v39
	v_div_fixup_f32 v34, v36, v34, 1.0
	v_pk_mul_f32 v[18:19], v[18:19], v[34:35]
	ds_write_b128 v104, v[16:19]
	v_pk_mul_f32 v[16:17], v[24:25], v[32:33]
	v_pk_mul_f32 v[18:19], v[30:31], v[34:35]
	ds_write_b128 v104, v[16:19] offset:1024
	v_pk_mul_f32 v[16:17], v[22:23], v[32:33]
	v_pk_mul_f32 v[18:19], v[28:29], v[34:35]
	ds_write_b128 v104, v[16:19] offset:2048
	v_pk_mul_f32 v[16:17], v[20:21], v[32:33]
	v_pk_mul_f32 v[18:19], v[26:27], v[34:35]
	ds_write_b128 v104, v[16:19] offset:3072
	s_addc_u32 s7, s7, s11
	v_lshrrev_b32_e32 v16, 2, v102
	v_lshl_add_u64 v[24:25], s[6:7], 0, v[192:193]
	v_and_b32_e32 v16, 12, v16
	s_add_i32 s6, 0, 0x1000
	v_add3_u32 v86, v103, v16, s6
	v_and_b32_e32 v16, 48, v102
	v_add3_u32 v87, v103, v16, 0
	v_mov_b32_e32 v16, 0
	s_movk_i32 s6, 0xffc0
	v_mov_b32_e32 v17, v16
	v_mov_b32_e32 v20, v16
	v_mov_b32_e32 v21, v16
	v_mov_b32_e32 v28, v16
	v_mov_b32_e32 v29, v16
	v_mov_b32_e32 v36, v16
	v_mov_b32_e32 v37, v16
	v_mov_b32_e32 v18, v16
	v_mov_b32_e32 v19, v16
	v_mov_b32_e32 v22, v16
	v_mov_b32_e32 v23, v16
	v_mov_b32_e32 v32, v16
	v_mov_b32_e32 v33, v16
	v_mov_b32_e32 v40, v16
	v_mov_b32_e32 v41, v16
	v_mov_b32_e32 v26, v16
	v_mov_b32_e32 v27, v16
	v_mov_b32_e32 v34, v16
	v_mov_b32_e32 v35, v16
	v_mov_b32_e32 v42, v16
	v_mov_b32_e32 v43, v16
	v_mov_b32_e32 v46, v16
	v_mov_b32_e32 v47, v16
	v_mov_b32_e32 v30, v16
	v_mov_b32_e32 v31, v16
	v_mov_b32_e32 v38, v16
	v_mov_b32_e32 v39, v16
	v_mov_b32_e32 v44, v16
	v_mov_b32_e32 v45, v16
	v_mov_b32_e32 v48, v16
	v_mov_b32_e32 v49, v16
